# kept version with the x_prompt convert loop using global_load instead of flat_load (same addresses, vmcnt-only wait)
# speedup vs baseline: 1.0376x; 1.0376x over previous
; #define NTLD(p) __builtin_nontemporal_load(p)
; __device__ __forceinline__ void p0_convert_row2(Frame& F, const float* xp_, int m0, int m1) {
;     const f32x4* xa = (const f32x4*)(xp_ + (size_t)m0 * DM) + F.lane; const f32x4* xb = (const f32x4*)(xp_ + (size_t)m1 * DM) + F.lane;
;     f32x4 va[4], vb[4]; float sa = 0.f, sb = 0.f;
; #pragma unroll
;     for (int j = 0; j < 4; ++j) { va[j] = NTLD(xa + 64 * j); vb[j] = NTLD(xb + 64 * j); }
; #pragma unroll
;     for (int j = 0; j < 4; ++j) { sa += (va[j][0] * va[j][0] + va[j][1] * va[j][1]) + (va[j][2] * va[j][2] + va[j][3] * va[j][3]); sb += (vb[j][0] * vb[j][0] + vb[j][1] * vb[j][1]) + (vb[j][2] * vb[j][2] + vb[j][3] * vb[j][3]); }
;     sa = wave_sum(sa); sb = wave_sum(sb);
;     if (F.lane == 0) { WSP(float, WS_RSTD)[m0] = 1.0f / sqrtf(sa * (1.0f / DM) + EPS); WSP(float, WS_RSTD)[m1] = 1.0f / sqrtf(sb * (1.0f / DM) + EPS); }
.LBB0_344:
	s_ashr_i32 s11, s10, 31
	s_lshl_b64 s[8:9], s[10:11], 12
	s_add_i32 s12, s10, 8
	v_lshl_add_u64 v[2:3], v[36:37], 0, s[8:9]
	s_ashr_i32 s13, s12, 31
	global_load_dwordx4 v[26:29], v[2:3], off nt
	global_load_dwordx4 v[18:21], v[2:3], off offset:1024 nt
	global_load_dwordx4 v[10:13], v[2:3], off offset:2048 nt
	s_lshl_b64 s[8:9], s[12:13], 12
	v_lshl_add_u64 v[48:49], v[36:37], 0, s[8:9]
	global_load_dwordx4 v[2:5], v[2:3], off offset:3072 nt
	s_nop 0
	global_load_dwordx4 v[30:33], v[48:49], off nt
	global_load_dwordx4 v[22:25], v[48:49], off offset:1024 nt
	global_load_dwordx4 v[14:17], v[48:49], off offset:2048 nt
	global_load_dwordx4 v[6:9], v[48:49], off offset:3072 nt
	s_waitcnt vmcnt(0)
	v_mul_f32_e32 v47, v27, v27
	v_mul_f32_e32 v48, v29, v29
	v_mul_f32_e32 v49, v19, v19
	v_mul_f32_e32 v50, v21, v21
	v_mul_f32_e32 v51, v11, v11
	v_mul_f32_e32 v52, v13, v13
	v_fmac_f32_e32 v47, v26, v26
	v_fmac_f32_e32 v48, v28, v28
	v_mul_f32_e32 v55, v31, v31
	v_mul_f32_e32 v56, v33, v33
	v_fmac_f32_e32 v49, v18, v18
	v_fmac_f32_e32 v50, v20, v20
	v_mul_f32_e32 v57, v23, v23
	v_mul_f32_e32 v58, v25, v25
	v_fmac_f32_e32 v51, v10, v10
	v_fmac_f32_e32 v52, v12, v12
	v_mul_f32_e32 v59, v15, v15
	v_mul_f32_e32 v60, v17, v17
	v_add_f32_e32 v47, v47, v48
	v_fmac_f32_e32 v55, v30, v30
	v_fmac_f32_e32 v56, v32, v32
	v_add_f32_e32 v48, v49, v50
	v_fmac_f32_e32 v57, v22, v22
	v_fmac_f32_e32 v58, v24, v24
	v_mul_f32_e32 v53, v3, v3
	v_mul_f32_e32 v54, v5, v5
	v_mul_f32_e32 v61, v7, v7
	v_mul_f32_e32 v62, v9, v9
	v_add_f32_e32 v49, v51, v52
	v_fmac_f32_e32 v59, v14, v14
	v_fmac_f32_e32 v60, v16, v16
	v_add_f32_e32 v51, v55, v56
	v_add_f32_e32 v47, v47, v48
	v_add_f32_e32 v48, v57, v58
	v_fmac_f32_e32 v53, v2, v2
	v_fmac_f32_e32 v54, v4, v4
	v_fmac_f32_e32 v61, v6, v6
	v_fmac_f32_e32 v62, v8, v8
	v_add_f32_e32 v52, v59, v60
	v_add_f32_e32 v48, v51, v48
	v_add_f32_e32 v50, v53, v54
	v_add_f32_e32 v53, v61, v62
	v_add_f32_e32 v47, v47, v49
	v_add_f32_e32 v48, v48, v52
	v_add_f32_e32 v47, v47, v50
	v_add_f32_e32 v48, v48, v53
	ds_bpermute_b32 v49, v1, v47
	ds_bpermute_b32 v50, v1, v48
	s_waitcnt lgkmcnt(1)
	v_add_f32_e32 v47, v47, v49
	s_waitcnt lgkmcnt(0)
	v_add_f32_e32 v48, v48, v50
	ds_bpermute_b32 v49, v40, v47
	ds_bpermute_b32 v50, v40, v48
	s_waitcnt lgkmcnt(1)
	v_add_f32_e32 v47, v47, v49
	s_waitcnt lgkmcnt(0)
	v_add_f32_e32 v48, v48, v50
	ds_bpermute_b32 v49, v41, v47
	ds_bpermute_b32 v50, v41, v48
	s_waitcnt lgkmcnt(1)
	v_add_f32_e32 v47, v47, v49
	s_waitcnt lgkmcnt(0)
	v_add_f32_e32 v48, v48, v50
	ds_bpermute_b32 v49, v42, v47
	ds_bpermute_b32 v50, v42, v48
	s_waitcnt lgkmcnt(1)
	v_add_f32_e32 v47, v47, v49
	s_waitcnt lgkmcnt(0)
	v_add_f32_e32 v48, v48, v50
	ds_bpermute_b32 v49, v43, v47
	ds_bpermute_b32 v51, v43, v48
	s_waitcnt lgkmcnt(1)
	v_add_f32_e32 v49, v47, v49
	s_waitcnt lgkmcnt(0)
	v_add_f32_e32 v47, v48, v51
	ds_bpermute_b32 v50, v44, v49
	ds_bpermute_b32 v48, v44, v47
	s_and_saveexec_b64 s[14:15], s[4:5]
	s_cbranch_execz .LBB0_343
	s_waitcnt lgkmcnt(1)
	v_add_f32_e32 v49, v49, v50
	v_fmamk_f32 v49, v49, 0x3a800000, v34
	v_mul_f32_e32 v50, 0x4f800000, v49
	v_cmp_gt_f32_e32 vcc, s17, v49
	s_waitcnt lgkmcnt(0)
	v_add_f32_e32 v47, v47, v48
	v_fmamk_f32 v47, v47, 0x3a800000, v34
	v_cndmask_b32_e32 v49, v49, v50, vcc
	v_sqrt_f32_e32 v50, v49
	s_lshl_b64 s[20:21], s[10:11], 2
	v_add_u32_e32 v51, -1, v50
	v_fma_f32 v53, -v51, v50, v49
	v_add_u32_e32 v52, 1, v50
	v_cmp_ge_f32_e64 s[8:9], 0, v53
	s_nop 1
	v_cndmask_b32_e64 v51, v50, v51, s[8:9]
	v_fma_f32 v50, -v52, v50, v49
	v_cmp_lt_f32_e64 s[8:9], 0, v50
	s_nop 1
	v_cndmask_b32_e64 v50, v51, v52, s[8:9]
	v_mul_f32_e32 v51, 0x37800000, v50
	v_cndmask_b32_e32 v50, v50, v51, vcc
	v_cmp_class_f32_e32 vcc, v49, v45
	s_nop 1
	v_cndmask_b32_e32 v49, v50, v49, vcc
	v_div_scale_f32 v50, s[8:9], v49, v49, 1.0
	v_rcp_f32_e32 v51, v50
	v_cmp_gt_f32_e64 s[8:9], s17, v47
	v_fma_f32 v48, -v50, v51, 1.0
	v_fmac_f32_e32 v51, v48, v51
	v_div_scale_f32 v48, vcc, 1.0, v49, 1.0
	v_mul_f32_e32 v52, v48, v51
	v_fma_f32 v53, -v50, v52, v48
	v_fmac_f32_e32 v52, v53, v51
	v_fma_f32 v48, -v50, v52, v48
	v_mul_f32_e32 v50, 0x4f800000, v47
	v_cndmask_b32_e64 v47, v47, v50, s[8:9]
	v_sqrt_f32_e32 v50, v47
	v_div_fmas_f32 v48, v48, v51, v52
	v_div_fixup_f32 v48, v48, v49, 1.0
	v_add_u32_e32 v49, -1, v50
	v_fma_f32 v51, -v49, v50, v47
	v_cmp_ge_f32_e32 vcc, 0, v51
	v_add_u32_e32 v51, 1, v50
	s_nop 0
	v_cndmask_b32_e32 v49, v50, v49, vcc
	v_fma_f32 v50, -v51, v50, v47
	v_cmp_lt_f32_e32 vcc, 0, v50
	s_nop 1
	v_cndmask_b32_e32 v49, v49, v51, vcc
	v_mul_f32_e32 v50, 0x37800000, v49
	v_cndmask_b32_e64 v49, v49, v50, s[8:9]
	v_cmp_class_f32_e32 vcc, v47, v45
	s_nop 1
	v_cndmask_b32_e32 v47, v49, v47, vcc
	v_div_scale_f32 v49, s[8:9], v47, v47, 1.0
	v_rcp_f32_e32 v50, v49
	s_add_u32 s8, s1, s20
	s_addc_u32 s9, s16, s21
	s_nop 1
	global_store_dword v35, v48, s[8:9]
	v_fma_f32 v48, -v49, v50, 1.0
	v_fmac_f32_e32 v50, v48, v50
	v_div_scale_f32 v48, vcc, 1.0, v47, 1.0
	v_mul_f32_e32 v51, v48, v50
	v_fma_f32 v52, -v49, v51, v48
	v_fmac_f32_e32 v51, v52, v50
	v_fma_f32 v48, -v49, v51, v48
	s_lshl_b64 s[8:9], s[12:13], 2
	v_div_fmas_f32 v48, v48, v50, v51
	s_add_u32 s8, s1, s8
	v_div_fixup_f32 v47, v48, v47, 1.0
	s_addc_u32 s9, s16, s9
	global_store_dword v35, v47, s[8:9]
	s_branch .LBB0_343
